# stack8: attention running-max as four interleaved v_max3 chains instead of one serial chain (on top of stack7)
# speedup vs baseline: 1.0237x; 1.0019x over previous
; DI float half_max(float x) { const auto rr = __builtin_amdgcn_permlane32_swap(__float_as_uint(x), __float_as_uint(x), false, false); return fmaxf(__uint_as_float(rr[0]), __uint_as_float(rr[1])); }
; DI void attn_unit(const bf16_t* Qb, const bf16_t* Kb, const bf16_t* Vt, bf16_t* MIX, int b, int h, int qb, char* lds, int tid_in) {
;     ...
;             float mx = p[0][0];
; #pragma unroll
;             for (int kb = 0; kb < 4; ++kb)
; #pragma unroll
;                 for (int i = 0; i < 16; ++i) mx = fmaxf(mx, p[kb][i]);
;             mx = half_max(mx);
;             if (t == 0 || __any(mx > 8.f)) {
;                 const float dl = (t == 0) ? mx : fmaxf(mx, 0.f);
;                 m_run += dl;
.LBB0_457:
	s_or_b64 exec, exec, s[56:57]
	v_max3_f32 v190, v82, v83, v84
	v_max3_f32 v191, v66, v67, v68
	v_max3_f32 v192, v50, v51, v52
	v_max3_f32 v190, v190, v85, v86
	v_max3_f32 v191, v191, v69, v70
	v_max3_f32 v192, v192, v53, v54
	v_max3_f32 v190, v190, v87, v88
	v_max3_f32 v191, v191, v71, v72
	v_max3_f32 v192, v192, v55, v56
	v_max3_f32 v193, v34, v35, v36
	v_max3_f32 v190, v190, v89, v90
	v_max3_f32 v191, v191, v73, v74
	v_max3_f32 v192, v192, v57, v58
	v_max3_f32 v193, v193, v37, v38
	v_max3_f32 v190, v190, v91, v92
	v_max3_f32 v191, v191, v75, v76
	v_max3_f32 v192, v192, v59, v60
	v_max3_f32 v193, v193, v39, v40
	v_max3_f32 v190, v190, v93, v94
	v_max3_f32 v191, v191, v77, v78
	v_max3_f32 v192, v192, v61, v62
	v_max3_f32 v193, v193, v41, v42
	v_max3_f32 v190, v190, v95, v96
	v_max3_f32 v191, v191, v79, v80
	v_max3_f32 v192, v192, v63, v64
	v_max3_f32 v193, v193, v43, v44
	v_max3_f32 v193, v193, v45, v46
	v_max3_f32 v193, v193, v47, v48
	v_max3_f32 v190, v190, v191, v97
	v_max3_f32 v192, v192, v193, v81
	v_max3_f32 v190, v190, v192, v65
	v_max_f32_e32 v190, v190, v49
	v_mov_b32_e32 v191, v190
	s_nop 1
	v_permlane32_swap_b32_e32 v190, v191
	v_max_f32_e32 v191, v191, v191
	v_max_f32_e32 v190, v190, v190
	s_cmp_lg_u32 s74, 0
	s_cselect_b64 s[56:57], -1, 0
	s_cmp_eq_u32 s74, 0
	v_max_f32_e32 v190, v190, v191
	s_cbranch_scc1 .LBB0_460
	s_mov_b32 s2, 0x41000000
	v_cmp_lt_f32_e32 vcc, s2, v190
	s_cbranch_vccz .LBB0_461
	v_max_f32_e32 v190, v190, v190
	v_max_f32_e32 v190, 0, v190
